# previous + GEMM K-loops: drop redundant lgkmcnt(0) after barrier and back-to-back setprio 0/1 pairs
# speedup vs baseline: 1.0136x; 1.0136x over previous
.LBB0_184:
	s_add_u32 s24, s28, 0xfffc0080
	s_addc_u32 s25, s29, -1
	s_add_i32 s67, 0, 0x10000
	s_cmp_eq_u32 s66, 12
	s_cselect_b32 s41, s57, s25
	s_cselect_b32 s40, s62, s24
	s_cselect_b32 s25, s55, s65
	s_cselect_b32 s24, s63, s64
	s_add_i32 s72, 0, 0x14000
	v_add_u32_e32 v144, s67, v159
	v_add_u32_e32 v180, s72, v159
	ds_read_b128 v[132:135], v144
	ds_read_b128 v[136:139], v144 offset:1024
	ds_read_b128 v[140:143], v144 offset:2048
	ds_read_b128 v[144:147], v144 offset:3072
	ds_read_b128 v[148:151], v180
	ds_read_b128 v[152:155], v180 offset:1024
	ds_read_b128 v[172:175], v180 offset:2048
	ds_read_b128 v[180:183], v180 offset:3072
	v_lshl_add_u64 v[252:253], s[28:29], 0, v[168:169]
	s_add_i32 m0, s84, 0xc000
	ds_read_b128 v[184:187], v246
	ds_read_b128 v[188:191], v246 offset:1024
	ds_read_b128 v[192:195], v246 offset:2048
	ds_read_b128 v[196:199], v246 offset:3072
	ds_read_b128 v[248:251], v246 offset:4096
	ds_read_b128 v[206:209], v246 offset:5120
	ds_read_b128 v[210:213], v246 offset:6144
	ds_read_b128 v[214:217], v246 offset:7168
	global_load_lds_dwordx4 v[252:253], off
	v_lshl_add_u64 v[252:253], s[28:29], 0, v[170:171]
	s_add_i32 m0, s84, 0xe000
	s_nop 0
	global_load_lds_dwordx4 v[252:253], off
	s_waitcnt vmcnt(8)
	s_waitcnt lgkmcnt(0)
	s_barrier
	s_setprio 1
	v_mfma_f32_16x16x32_bf16 v[128:131], v[132:135], v[184:187], v[128:131]
	v_mfma_f32_16x16x32_bf16 v[124:127], v[140:143], v[184:187], v[124:127]
	v_mfma_f32_16x16x32_bf16 v[112:115], v[132:135], v[192:195], v[112:115]
	v_mfma_f32_16x16x32_bf16 v[108:111], v[140:143], v[192:195], v[108:111]
	v_mfma_f32_16x16x32_bf16 v[96:99], v[132:135], v[248:251], v[96:99]
	v_mfma_f32_16x16x32_bf16 v[92:95], v[140:143], v[248:251], v[92:95]
	v_mfma_f32_16x16x32_bf16 v[80:83], v[132:135], v[210:213], v[80:83]
	v_mfma_f32_16x16x32_bf16 v[76:79], v[140:143], v[210:213], v[76:79]
	v_mfma_f32_16x16x32_bf16 v[128:131], v[136:139], v[188:191], v[128:131]
	v_mfma_f32_16x16x32_bf16 v[124:127], v[144:147], v[188:191], v[124:127]
	v_mfma_f32_16x16x32_bf16 v[112:115], v[136:139], v[196:199], v[112:115]
	v_mfma_f32_16x16x32_bf16 v[108:111], v[144:147], v[196:199], v[108:111]
	v_mfma_f32_16x16x32_bf16 v[96:99], v[136:139], v[206:209], v[96:99]
	v_mfma_f32_16x16x32_bf16 v[92:95], v[144:147], v[206:209], v[92:95]
	v_mfma_f32_16x16x32_bf16 v[80:83], v[136:139], v[214:217], v[80:83]
	v_mfma_f32_16x16x32_bf16 v[76:79], v[144:147], v[214:217], v[76:79]
	v_mfma_f32_16x16x32_bf16 v[120:123], v[148:151], v[184:187], v[120:123]
	v_mfma_f32_16x16x32_bf16 v[116:119], v[172:175], v[184:187], v[116:119]
	v_mfma_f32_16x16x32_bf16 v[104:107], v[148:151], v[192:195], v[104:107]
	v_mfma_f32_16x16x32_bf16 v[100:103], v[172:175], v[192:195], v[100:103]
	v_mfma_f32_16x16x32_bf16 v[88:91], v[148:151], v[248:251], v[88:91]
	v_mfma_f32_16x16x32_bf16 v[84:87], v[172:175], v[248:251], v[84:87]
	v_mfma_f32_16x16x32_bf16 v[72:75], v[148:151], v[210:213], v[72:75]
	v_mfma_f32_16x16x32_bf16 v[68:71], v[172:175], v[210:213], v[68:71]
	v_mfma_f32_16x16x32_bf16 v[120:123], v[152:155], v[188:191], v[120:123]
	v_mfma_f32_16x16x32_bf16 v[116:119], v[180:183], v[188:191], v[116:119]
	v_mfma_f32_16x16x32_bf16 v[104:107], v[152:155], v[196:199], v[104:107]
	v_mfma_f32_16x16x32_bf16 v[100:103], v[180:183], v[196:199], v[100:103]
	v_mfma_f32_16x16x32_bf16 v[88:91], v[152:155], v[206:209], v[88:91]
	v_mfma_f32_16x16x32_bf16 v[84:87], v[180:183], v[206:209], v[84:87]
	v_mfma_f32_16x16x32_bf16 v[72:75], v[152:155], v[214:217], v[72:75]
	v_mfma_f32_16x16x32_bf16 v[68:71], v[180:183], v[214:217], v[68:71]
	s_setprio 0
	s_barrier
	s_add_i32 s67, s67, s3
	v_lshl_add_u64 v[252:253], s[24:25], 0, v[156:157]
	s_mov_b32 m0, s67
	ds_read_b128 v[184:187], v246 offset:16384
	ds_read_b128 v[188:191], v246 offset:17408
	ds_read_b128 v[192:195], v246 offset:18432
	ds_read_b128 v[196:199], v246 offset:19456
	ds_read_b128 v[206:209], v246 offset:20480
	ds_read_b128 v[210:213], v246 offset:21504
	ds_read_b128 v[214:217], v246 offset:22528
	ds_read_b128 v[248:251], v246 offset:23552
	global_load_lds_dwordx4 v[252:253], off
	s_add_i32 m0, s67, 0x2000
	s_add_u32 s96, s24, 0x40000
	v_lshl_add_u64 v[218:219], s[24:25], 0, v[0:1]
	s_addc_u32 s97, s25, 0
	s_add_i32 s67, s72, s3
	global_load_lds_dwordx4 v[218:219], off
	v_lshl_add_u64 v[220:221], s[96:97], 0, v[156:157]
	s_mov_b32 m0, s67
	v_lshl_add_u64 v[222:223], s[40:41], 0, v[0:1]
	global_load_lds_dwordx4 v[220:221], off
	v_lshl_add_u64 v[220:221], s[96:97], 0, v[0:1]
	s_add_i32 m0, s67, 0x2000
	s_nop 0
	global_load_lds_dwordx4 v[220:221], off
	v_lshl_add_u64 v[220:221], s[40:41], 0, v[156:157]
	s_mov_b32 m0, s84
	s_nop 0
	global_load_lds_dwordx4 v[220:221], off
	s_mov_b32 m0, s85
	s_nop 0
	global_load_lds_dwordx4 v[222:223], off
	s_waitcnt vmcnt(8)
	s_waitcnt lgkmcnt(0)
	s_barrier
	s_setprio 1
	v_mfma_f32_16x16x32_bf16 v[64:67], v[132:135], v[184:187], v[64:67]
	v_mfma_f32_16x16x32_bf16 v[60:63], v[140:143], v[184:187], v[60:63]
	v_mfma_f32_16x16x32_bf16 v[48:51], v[132:135], v[192:195], v[48:51]
	v_mfma_f32_16x16x32_bf16 v[44:47], v[140:143], v[192:195], v[44:47]
	v_mfma_f32_16x16x32_bf16 v[32:35], v[132:135], v[206:209], v[32:35]
	v_mfma_f32_16x16x32_bf16 v[28:31], v[140:143], v[206:209], v[28:31]
	v_mfma_f32_16x16x32_bf16 v[16:19], v[132:135], v[214:217], v[16:19]
	v_mfma_f32_16x16x32_bf16 v[12:15], v[140:143], v[214:217], v[12:15]
	v_mfma_f32_16x16x32_bf16 v[64:67], v[136:139], v[188:191], v[64:67]
	v_mfma_f32_16x16x32_bf16 v[60:63], v[144:147], v[188:191], v[60:63]
	v_mfma_f32_16x16x32_bf16 v[48:51], v[136:139], v[196:199], v[48:51]
	v_mfma_f32_16x16x32_bf16 v[44:47], v[144:147], v[196:199], v[44:47]
	v_mfma_f32_16x16x32_bf16 v[32:35], v[136:139], v[210:213], v[32:35]
	v_mfma_f32_16x16x32_bf16 v[28:31], v[144:147], v[210:213], v[28:31]
	v_mfma_f32_16x16x32_bf16 v[16:19], v[136:139], v[248:251], v[16:19]
	v_mfma_f32_16x16x32_bf16 v[12:15], v[144:147], v[248:251], v[12:15]
	v_mfma_f32_16x16x32_bf16 v[56:59], v[148:151], v[184:187], v[56:59]
	v_mfma_f32_16x16x32_bf16 v[52:55], v[172:175], v[184:187], v[52:55]
	v_mfma_f32_16x16x32_bf16 v[40:43], v[148:151], v[192:195], v[40:43]
	v_mfma_f32_16x16x32_bf16 v[36:39], v[172:175], v[192:195], v[36:39]
	v_mfma_f32_16x16x32_bf16 v[24:27], v[148:151], v[206:209], v[24:27]
	v_mfma_f32_16x16x32_bf16 v[20:23], v[172:175], v[206:209], v[20:23]
	v_mfma_f32_16x16x32_bf16 v[8:11], v[148:151], v[214:217], v[8:11]
	v_mfma_f32_16x16x32_bf16 v[4:7], v[172:175], v[214:217], v[4:7]
	v_mfma_f32_16x16x32_bf16 v[56:59], v[152:155], v[188:191], v[56:59]
	v_mfma_f32_16x16x32_bf16 v[52:55], v[180:183], v[188:191], v[52:55]
	v_mfma_f32_16x16x32_bf16 v[40:43], v[152:155], v[196:199], v[40:43]
	v_mfma_f32_16x16x32_bf16 v[36:39], v[180:183], v[196:199], v[36:39]
	v_mfma_f32_16x16x32_bf16 v[24:27], v[152:155], v[210:213], v[24:27]
	v_mfma_f32_16x16x32_bf16 v[20:23], v[180:183], v[210:213], v[20:23]
	v_mfma_f32_16x16x32_bf16 v[8:11], v[152:155], v[248:251], v[8:11]
	v_mfma_f32_16x16x32_bf16 v[4:7], v[180:183], v[248:251], v[4:7]
	s_setprio 0
	s_barrier
	s_add_i32 s67, 0, 0x18000
	s_add_i32 s72, 0, 0x1c000
	v_add_u32_e32 v144, s67, v159
	v_add_u32_e32 v180, s72, v159
	ds_read_b128 v[132:135], v144
	ds_read_b128 v[136:139], v144 offset:1024
	ds_read_b128 v[140:143], v144 offset:2048
	ds_read_b128 v[144:147], v144 offset:3072
	ds_read_b128 v[148:151], v180
	ds_read_b128 v[152:155], v180 offset:1024
	ds_read_b128 v[172:175], v180 offset:2048
	ds_read_b128 v[180:183], v180 offset:3072
	s_add_u32 s40, s40, 0x40000
	s_addc_u32 s41, s41, 0
	s_mov_b32 m0, s86
	v_lshl_add_u64 v[224:225], s[40:41], 0, v[156:157]
	ds_read_b128 v[184:187], v246 offset:32768
	ds_read_b128 v[188:191], v246 offset:33792
	ds_read_b128 v[192:195], v246 offset:34816
	ds_read_b128 v[196:199], v246 offset:35840
	ds_read_b128 v[206:209], v246 offset:36864
	ds_read_b128 v[210:213], v246 offset:37888
	ds_read_b128 v[214:217], v246 offset:38912
	ds_read_b128 v[248:251], v246 offset:39936
	global_load_lds_dwordx4 v[224:225], off
	v_lshl_add_u64 v[224:225], s[40:41], 0, v[0:1]
	s_mov_b32 m0, s87
	s_nop 0
	global_load_lds_dwordx4 v[224:225], off
	s_waitcnt vmcnt(8)
	s_waitcnt lgkmcnt(0)
	s_barrier
	s_setprio 1
	v_mfma_f32_16x16x32_bf16 v[128:131], v[132:135], v[184:187], v[128:131]
	v_mfma_f32_16x16x32_bf16 v[124:127], v[140:143], v[184:187], v[124:127]
	v_mfma_f32_16x16x32_bf16 v[112:115], v[132:135], v[192:195], v[112:115]
	v_mfma_f32_16x16x32_bf16 v[108:111], v[140:143], v[192:195], v[108:111]
	v_mfma_f32_16x16x32_bf16 v[96:99], v[132:135], v[206:209], v[96:99]
	v_mfma_f32_16x16x32_bf16 v[92:95], v[140:143], v[206:209], v[92:95]
	v_mfma_f32_16x16x32_bf16 v[80:83], v[132:135], v[214:217], v[80:83]
	v_mfma_f32_16x16x32_bf16 v[76:79], v[140:143], v[214:217], v[76:79]
	v_mfma_f32_16x16x32_bf16 v[128:131], v[136:139], v[188:191], v[128:131]
	v_mfma_f32_16x16x32_bf16 v[124:127], v[144:147], v[188:191], v[124:127]
	v_mfma_f32_16x16x32_bf16 v[112:115], v[136:139], v[196:199], v[112:115]
	v_mfma_f32_16x16x32_bf16 v[108:111], v[144:147], v[196:199], v[108:111]
	v_mfma_f32_16x16x32_bf16 v[96:99], v[136:139], v[210:213], v[96:99]
	v_mfma_f32_16x16x32_bf16 v[92:95], v[144:147], v[210:213], v[92:95]
	v_mfma_f32_16x16x32_bf16 v[80:83], v[136:139], v[248:251], v[80:83]
	v_mfma_f32_16x16x32_bf16 v[76:79], v[144:147], v[248:251], v[76:79]
	v_mfma_f32_16x16x32_bf16 v[120:123], v[148:151], v[184:187], v[120:123]
	v_mfma_f32_16x16x32_bf16 v[116:119], v[172:175], v[184:187], v[116:119]
	v_mfma_f32_16x16x32_bf16 v[104:107], v[148:151], v[192:195], v[104:107]
	v_mfma_f32_16x16x32_bf16 v[100:103], v[172:175], v[192:195], v[100:103]
	v_mfma_f32_16x16x32_bf16 v[88:91], v[148:151], v[206:209], v[88:91]
	v_mfma_f32_16x16x32_bf16 v[84:87], v[172:175], v[206:209], v[84:87]
	v_mfma_f32_16x16x32_bf16 v[72:75], v[148:151], v[214:217], v[72:75]
	v_mfma_f32_16x16x32_bf16 v[68:71], v[172:175], v[214:217], v[68:71]
	v_mfma_f32_16x16x32_bf16 v[120:123], v[152:155], v[188:191], v[120:123]
	v_mfma_f32_16x16x32_bf16 v[116:119], v[180:183], v[188:191], v[116:119]
	v_mfma_f32_16x16x32_bf16 v[104:107], v[152:155], v[196:199], v[104:107]
	v_mfma_f32_16x16x32_bf16 v[100:103], v[180:183], v[196:199], v[100:103]
	v_mfma_f32_16x16x32_bf16 v[88:91], v[152:155], v[210:213], v[88:91]
	v_mfma_f32_16x16x32_bf16 v[84:87], v[180:183], v[210:213], v[84:87]
	v_mfma_f32_16x16x32_bf16 v[72:75], v[152:155], v[248:251], v[72:75]
	v_mfma_f32_16x16x32_bf16 v[68:71], v[180:183], v[248:251], v[68:71]
	s_setprio 0
	s_barrier
	s_add_i32 s40, s67, s3
	v_lshl_add_u64 v[224:225], v[252:253], 0, s[30:31]
	s_mov_b32 m0, s40
	ds_read_b128 v[184:187], v246 offset:49152
	ds_read_b128 v[188:191], v246 offset:50176
	ds_read_b128 v[192:195], v246 offset:51200
	ds_read_b128 v[196:199], v246 offset:52224
	ds_read_b128 v[206:209], v246 offset:53248
	ds_read_b128 v[210:213], v246 offset:54272
	ds_read_b128 v[214:217], v246 offset:55296
	ds_read_b128 v[248:251], v246 offset:56320
	global_load_lds_dwordx4 v[224:225], off
	s_add_i32 m0, s40, 0x2000
	s_add_u32 s24, s24, 0x40080
	v_lshl_add_u64 v[218:219], v[218:219], 0, s[30:31]
	s_addc_u32 s25, s25, 0
	s_add_i32 s40, s72, s3
	global_load_lds_dwordx4 v[218:219], off
	v_lshl_add_u64 v[218:219], s[24:25], 0, v[156:157]
	s_mov_b32 m0, s40
	s_nop 0
	global_load_lds_dwordx4 v[218:219], off
	v_lshl_add_u64 v[218:219], s[24:25], 0, v[0:1]
	s_add_i32 m0, s40, 0x2000
	s_nop 0
	global_load_lds_dwordx4 v[218:219], off
	v_lshl_add_u64 v[218:219], v[220:221], 0, s[30:31]
	s_mov_b32 m0, s92
	s_nop 0
	global_load_lds_dwordx4 v[218:219], off
	v_lshl_add_u64 v[218:219], v[222:223], 0, s[30:31]
	s_mov_b32 m0, s93
	s_nop 0
	global_load_lds_dwordx4 v[218:219], off
	s_waitcnt vmcnt(8)
	s_waitcnt lgkmcnt(0)
	s_barrier
	s_setprio 1
	v_mfma_f32_16x16x32_bf16 v[64:67], v[132:135], v[184:187], v[64:67]
	v_mfma_f32_16x16x32_bf16 v[60:63], v[140:143], v[184:187], v[60:63]
	v_mfma_f32_16x16x32_bf16 v[48:51], v[132:135], v[192:195], v[48:51]
	v_mfma_f32_16x16x32_bf16 v[44:47], v[140:143], v[192:195], v[44:47]
	v_mfma_f32_16x16x32_bf16 v[32:35], v[132:135], v[206:209], v[32:35]
	v_mfma_f32_16x16x32_bf16 v[28:31], v[140:143], v[206:209], v[28:31]
	v_mfma_f32_16x16x32_bf16 v[16:19], v[132:135], v[214:217], v[16:19]
	v_mfma_f32_16x16x32_bf16 v[12:15], v[140:143], v[214:217], v[12:15]
	v_mfma_f32_16x16x32_bf16 v[64:67], v[136:139], v[188:191], v[64:67]
	v_mfma_f32_16x16x32_bf16 v[60:63], v[144:147], v[188:191], v[60:63]
	v_mfma_f32_16x16x32_bf16 v[48:51], v[136:139], v[196:199], v[48:51]
	v_mfma_f32_16x16x32_bf16 v[44:47], v[144:147], v[196:199], v[44:47]
	v_mfma_f32_16x16x32_bf16 v[32:35], v[136:139], v[210:213], v[32:35]
	v_mfma_f32_16x16x32_bf16 v[28:31], v[144:147], v[210:213], v[28:31]
	v_mfma_f32_16x16x32_bf16 v[16:19], v[136:139], v[248:251], v[16:19]
	v_mfma_f32_16x16x32_bf16 v[12:15], v[144:147], v[248:251], v[12:15]
	v_mfma_f32_16x16x32_bf16 v[56:59], v[148:151], v[184:187], v[56:59]
	v_mfma_f32_16x16x32_bf16 v[52:55], v[172:175], v[184:187], v[52:55]
	v_mfma_f32_16x16x32_bf16 v[40:43], v[148:151], v[192:195], v[40:43]
	v_mfma_f32_16x16x32_bf16 v[36:39], v[172:175], v[192:195], v[36:39]
	v_mfma_f32_16x16x32_bf16 v[24:27], v[148:151], v[206:209], v[24:27]
	v_mfma_f32_16x16x32_bf16 v[20:23], v[172:175], v[206:209], v[20:23]
	v_mfma_f32_16x16x32_bf16 v[8:11], v[148:151], v[214:217], v[8:11]
	v_mfma_f32_16x16x32_bf16 v[4:7], v[172:175], v[214:217], v[4:7]
	v_mfma_f32_16x16x32_bf16 v[56:59], v[152:155], v[188:191], v[56:59]
	v_mfma_f32_16x16x32_bf16 v[52:55], v[180:183], v[188:191], v[52:55]
	v_mfma_f32_16x16x32_bf16 v[40:43], v[152:155], v[196:199], v[40:43]
	v_mfma_f32_16x16x32_bf16 v[36:39], v[180:183], v[196:199], v[36:39]
	v_mfma_f32_16x16x32_bf16 v[24:27], v[152:155], v[210:213], v[24:27]
	v_mfma_f32_16x16x32_bf16 v[20:23], v[180:183], v[210:213], v[20:23]
	v_mfma_f32_16x16x32_bf16 v[8:11], v[152:155], v[248:251], v[8:11]
	v_mfma_f32_16x16x32_bf16 v[4:7], v[180:183], v[248:251], v[4:7]
	s_setprio 0
	s_barrier
	s_add_i32 s66, s66, 2
	s_add_u32 s28, s28, 0x100
	s_addc_u32 s29, s29, 0
	s_add_u32 s64, s64, 0x100
	s_addc_u32 s65, s65, 0
	s_cmp_gt_u32 s66, 13
	s_cbranch_scc0 .LBB0_184
	s_and_b64 vcc, exec, s[52:53]
	s_cbranch_vccz .LBB0_187
	s_barrier

.LBB0_800:
	s_add_u32 s64, s62, 0x100
	s_addc_u32 s65, s63, 0
	s_add_i32 s72, 0, 0x10000
	s_cmp_eq_u32 s96, 12
	s_cselect_b32 s67, s57, s65
	s_cselect_b32 s66, s92, s64
	v_add_u32_e32 v145, s72, v142
	s_cselect_b32 s25, s55, s95
	s_cselect_b32 s24, s93, s94
	s_add_i32 s73, 0, 0x14000
	ds_read_b128 v[138:141], v145
	ds_read_b128 v[146:149], v145 offset:1024
	ds_read_b128 v[150:153], v145 offset:2048
	ds_read_b128 v[154:157], v145 offset:3072
	v_add_u32_e32 v145, s73, v142
	ds_read_b128 v[158:161], v145
	ds_read_b128 v[162:165], v145 offset:1024
	ds_read_b128 v[166:169], v145 offset:2048
	ds_read_b128 v[170:173], v145 offset:3072
	v_lshl_add_u64 v[174:175], s[62:63], 0, v[134:135]
	s_add_i32 m0, s84, 0xc000
	ds_read_b128 v[180:183], v144
	ds_read_b128 v[184:187], v144 offset:1024
	ds_read_b128 v[188:191], v144 offset:2048
	ds_read_b128 v[192:195], v144 offset:3072
	ds_read_b128 v[196:199], v144 offset:4096
	ds_read_b128 v[206:209], v144 offset:5120
	ds_read_b128 v[210:213], v144 offset:6144
	ds_read_b128 v[214:217], v144 offset:7168
	global_load_lds_dwordx4 v[174:175], off
	v_lshl_add_u64 v[174:175], s[62:63], 0, v[136:137]
	s_add_i32 m0, s84, 0xe000
	s_nop 0
	global_load_lds_dwordx4 v[174:175], off
	s_waitcnt vmcnt(8)
	s_waitcnt lgkmcnt(0)
	s_barrier
	s_setprio 1
	v_mfma_f32_16x16x32_bf16 v[128:131], v[138:141], v[180:183], v[128:131]
	v_mfma_f32_16x16x32_bf16 v[124:127], v[150:153], v[180:183], v[124:127]
	v_mfma_f32_16x16x32_bf16 v[112:115], v[138:141], v[188:191], v[112:115]
	v_mfma_f32_16x16x32_bf16 v[108:111], v[150:153], v[188:191], v[108:111]
	v_mfma_f32_16x16x32_bf16 v[96:99], v[138:141], v[196:199], v[96:99]
	v_mfma_f32_16x16x32_bf16 v[92:95], v[150:153], v[196:199], v[92:95]
	v_mfma_f32_16x16x32_bf16 v[80:83], v[138:141], v[210:213], v[80:83]
	v_mfma_f32_16x16x32_bf16 v[76:79], v[150:153], v[210:213], v[76:79]
	v_mfma_f32_16x16x32_bf16 v[128:131], v[146:149], v[184:187], v[128:131]
	v_mfma_f32_16x16x32_bf16 v[124:127], v[154:157], v[184:187], v[124:127]
	v_mfma_f32_16x16x32_bf16 v[112:115], v[146:149], v[192:195], v[112:115]
	v_mfma_f32_16x16x32_bf16 v[108:111], v[154:157], v[192:195], v[108:111]
	v_mfma_f32_16x16x32_bf16 v[96:99], v[146:149], v[206:209], v[96:99]
	v_mfma_f32_16x16x32_bf16 v[92:95], v[154:157], v[206:209], v[92:95]
	v_mfma_f32_16x16x32_bf16 v[80:83], v[146:149], v[214:217], v[80:83]
	v_mfma_f32_16x16x32_bf16 v[76:79], v[154:157], v[214:217], v[76:79]
	v_mfma_f32_16x16x32_bf16 v[120:123], v[158:161], v[180:183], v[120:123]
	v_mfma_f32_16x16x32_bf16 v[116:119], v[166:169], v[180:183], v[116:119]
	v_mfma_f32_16x16x32_bf16 v[104:107], v[158:161], v[188:191], v[104:107]
	v_mfma_f32_16x16x32_bf16 v[100:103], v[166:169], v[188:191], v[100:103]
	v_mfma_f32_16x16x32_bf16 v[88:91], v[158:161], v[196:199], v[88:91]
	v_mfma_f32_16x16x32_bf16 v[84:87], v[166:169], v[196:199], v[84:87]
	v_mfma_f32_16x16x32_bf16 v[72:75], v[158:161], v[210:213], v[72:75]
	v_mfma_f32_16x16x32_bf16 v[68:71], v[166:169], v[210:213], v[68:71]
	v_mfma_f32_16x16x32_bf16 v[120:123], v[162:165], v[184:187], v[120:123]
	v_mfma_f32_16x16x32_bf16 v[116:119], v[170:173], v[184:187], v[116:119]
	v_mfma_f32_16x16x32_bf16 v[104:107], v[162:165], v[192:195], v[104:107]
	v_mfma_f32_16x16x32_bf16 v[100:103], v[170:173], v[192:195], v[100:103]
	v_mfma_f32_16x16x32_bf16 v[88:91], v[162:165], v[206:209], v[88:91]
	v_mfma_f32_16x16x32_bf16 v[84:87], v[170:173], v[206:209], v[84:87]
	v_mfma_f32_16x16x32_bf16 v[72:75], v[162:165], v[214:217], v[72:75]
	v_mfma_f32_16x16x32_bf16 v[68:71], v[170:173], v[214:217], v[68:71]
	s_setprio 0
	s_barrier
	s_add_i32 s62, s72, s71
	v_lshl_add_u64 v[174:175], s[24:25], 0, v[132:133]
	s_mov_b32 m0, s62
	ds_read_b128 v[180:183], v144 offset:16384
	ds_read_b128 v[184:187], v144 offset:17408
	ds_read_b128 v[188:191], v144 offset:18432
	ds_read_b128 v[192:195], v144 offset:19456
	ds_read_b128 v[196:199], v144 offset:20480
	ds_read_b128 v[206:209], v144 offset:21504
	ds_read_b128 v[210:213], v144 offset:22528
	ds_read_b128 v[214:217], v144 offset:23552
	global_load_lds_dwordx4 v[174:175], off
	s_add_i32 m0, s62, 0x2000
	s_add_u32 s62, s24, 0x40000
	v_lshl_add_u64 v[218:219], s[24:25], 0, v[0:1]
	s_addc_u32 s63, s25, 0
	s_add_i32 s72, s73, s71
	global_load_lds_dwordx4 v[218:219], off
	v_lshl_add_u64 v[220:221], s[62:63], 0, v[132:133]
	s_mov_b32 m0, s72
	v_lshl_add_u64 v[222:223], s[66:67], 0, v[0:1]
	global_load_lds_dwordx4 v[220:221], off
	v_lshl_add_u64 v[220:221], s[62:63], 0, v[0:1]
	s_add_i32 m0, s72, 0x2000
	s_nop 0
	global_load_lds_dwordx4 v[220:221], off
	v_lshl_add_u64 v[220:221], s[66:67], 0, v[132:133]
	s_mov_b32 m0, s84
	s_nop 0
	global_load_lds_dwordx4 v[220:221], off
	s_mov_b32 m0, s85
	s_nop 0
	global_load_lds_dwordx4 v[222:223], off
	s_waitcnt vmcnt(8)
	s_waitcnt lgkmcnt(0)
	s_barrier
	s_setprio 1
	v_mfma_f32_16x16x32_bf16 v[64:67], v[138:141], v[180:183], v[64:67]
	v_mfma_f32_16x16x32_bf16 v[60:63], v[150:153], v[180:183], v[60:63]
	v_mfma_f32_16x16x32_bf16 v[48:51], v[138:141], v[188:191], v[48:51]
	v_mfma_f32_16x16x32_bf16 v[44:47], v[150:153], v[188:191], v[44:47]
	v_mfma_f32_16x16x32_bf16 v[32:35], v[138:141], v[196:199], v[32:35]
	v_mfma_f32_16x16x32_bf16 v[28:31], v[150:153], v[196:199], v[28:31]
	v_mfma_f32_16x16x32_bf16 v[16:19], v[138:141], v[210:213], v[16:19]
	v_mfma_f32_16x16x32_bf16 v[12:15], v[150:153], v[210:213], v[12:15]
	v_mfma_f32_16x16x32_bf16 v[64:67], v[146:149], v[184:187], v[64:67]
	v_mfma_f32_16x16x32_bf16 v[60:63], v[154:157], v[184:187], v[60:63]
	v_mfma_f32_16x16x32_bf16 v[48:51], v[146:149], v[192:195], v[48:51]
	v_mfma_f32_16x16x32_bf16 v[44:47], v[154:157], v[192:195], v[44:47]
	v_mfma_f32_16x16x32_bf16 v[32:35], v[146:149], v[206:209], v[32:35]
	v_mfma_f32_16x16x32_bf16 v[28:31], v[154:157], v[206:209], v[28:31]
	v_mfma_f32_16x16x32_bf16 v[16:19], v[146:149], v[214:217], v[16:19]
	v_mfma_f32_16x16x32_bf16 v[12:15], v[154:157], v[214:217], v[12:15]
	v_mfma_f32_16x16x32_bf16 v[56:59], v[158:161], v[180:183], v[56:59]
	v_mfma_f32_16x16x32_bf16 v[52:55], v[166:169], v[180:183], v[52:55]
	v_mfma_f32_16x16x32_bf16 v[40:43], v[158:161], v[188:191], v[40:43]
	v_mfma_f32_16x16x32_bf16 v[36:39], v[166:169], v[188:191], v[36:39]
	v_mfma_f32_16x16x32_bf16 v[24:27], v[158:161], v[196:199], v[24:27]
	v_mfma_f32_16x16x32_bf16 v[20:23], v[166:169], v[196:199], v[20:23]
	v_mfma_f32_16x16x32_bf16 v[8:11], v[158:161], v[210:213], v[8:11]
	v_mfma_f32_16x16x32_bf16 v[4:7], v[166:169], v[210:213], v[4:7]
	v_mfma_f32_16x16x32_bf16 v[56:59], v[162:165], v[184:187], v[56:59]
	v_mfma_f32_16x16x32_bf16 v[52:55], v[170:173], v[184:187], v[52:55]
	v_mfma_f32_16x16x32_bf16 v[40:43], v[162:165], v[192:195], v[40:43]
	v_mfma_f32_16x16x32_bf16 v[36:39], v[170:173], v[192:195], v[36:39]
	v_mfma_f32_16x16x32_bf16 v[24:27], v[162:165], v[206:209], v[24:27]
	v_mfma_f32_16x16x32_bf16 v[20:23], v[170:173], v[206:209], v[20:23]
	v_mfma_f32_16x16x32_bf16 v[8:11], v[162:165], v[214:217], v[8:11]
	v_mfma_f32_16x16x32_bf16 v[4:7], v[170:173], v[214:217], v[4:7]
	s_setprio 0
	s_barrier
	s_add_i32 s72, 0, 0x18000
	v_add_u32_e32 v145, s72, v142
	s_add_i32 s73, 0, 0x1c000
	ds_read_b128 v[138:141], v145
	ds_read_b128 v[146:149], v145 offset:1024
	ds_read_b128 v[150:153], v145 offset:2048
	ds_read_b128 v[154:157], v145 offset:3072
	v_add_u32_e32 v145, s73, v142
	ds_read_b128 v[158:161], v145
	ds_read_b128 v[162:165], v145 offset:1024
	ds_read_b128 v[166:169], v145 offset:2048
	ds_read_b128 v[170:173], v145 offset:3072
	s_add_u32 s62, s66, 0x40000
	s_addc_u32 s63, s67, 0
	s_mov_b32 m0, s86
	v_lshl_add_u64 v[224:225], s[62:63], 0, v[132:133]
	ds_read_b128 v[180:183], v144 offset:32768
	ds_read_b128 v[184:187], v144 offset:33792
	ds_read_b128 v[188:191], v144 offset:34816
	ds_read_b128 v[192:195], v144 offset:35840
	ds_read_b128 v[196:199], v144 offset:36864
	ds_read_b128 v[206:209], v144 offset:37888
	ds_read_b128 v[210:213], v144 offset:38912
	ds_read_b128 v[214:217], v144 offset:39936
	global_load_lds_dwordx4 v[224:225], off
	v_lshl_add_u64 v[224:225], s[62:63], 0, v[0:1]
	s_mov_b32 m0, s87
	s_nop 0
	global_load_lds_dwordx4 v[224:225], off
	s_waitcnt vmcnt(8)
	s_waitcnt lgkmcnt(0)
	s_barrier
	s_setprio 1
	v_mfma_f32_16x16x32_bf16 v[128:131], v[138:141], v[180:183], v[128:131]
	v_mfma_f32_16x16x32_bf16 v[124:127], v[150:153], v[180:183], v[124:127]
	v_mfma_f32_16x16x32_bf16 v[112:115], v[138:141], v[188:191], v[112:115]
	v_mfma_f32_16x16x32_bf16 v[108:111], v[150:153], v[188:191], v[108:111]
	v_mfma_f32_16x16x32_bf16 v[96:99], v[138:141], v[196:199], v[96:99]
	v_mfma_f32_16x16x32_bf16 v[92:95], v[150:153], v[196:199], v[92:95]
	v_mfma_f32_16x16x32_bf16 v[80:83], v[138:141], v[210:213], v[80:83]
	v_mfma_f32_16x16x32_bf16 v[76:79], v[150:153], v[210:213], v[76:79]
	v_mfma_f32_16x16x32_bf16 v[128:131], v[146:149], v[184:187], v[128:131]
	v_mfma_f32_16x16x32_bf16 v[124:127], v[154:157], v[184:187], v[124:127]
	v_mfma_f32_16x16x32_bf16 v[112:115], v[146:149], v[192:195], v[112:115]
	v_mfma_f32_16x16x32_bf16 v[108:111], v[154:157], v[192:195], v[108:111]
	v_mfma_f32_16x16x32_bf16 v[96:99], v[146:149], v[206:209], v[96:99]
	v_mfma_f32_16x16x32_bf16 v[92:95], v[154:157], v[206:209], v[92:95]
	v_mfma_f32_16x16x32_bf16 v[80:83], v[146:149], v[214:217], v[80:83]
	v_mfma_f32_16x16x32_bf16 v[76:79], v[154:157], v[214:217], v[76:79]
	v_mfma_f32_16x16x32_bf16 v[120:123], v[158:161], v[180:183], v[120:123]
	v_mfma_f32_16x16x32_bf16 v[116:119], v[166:169], v[180:183], v[116:119]
	v_mfma_f32_16x16x32_bf16 v[104:107], v[158:161], v[188:191], v[104:107]
	v_mfma_f32_16x16x32_bf16 v[100:103], v[166:169], v[188:191], v[100:103]
	v_mfma_f32_16x16x32_bf16 v[88:91], v[158:161], v[196:199], v[88:91]
	v_mfma_f32_16x16x32_bf16 v[84:87], v[166:169], v[196:199], v[84:87]
	v_mfma_f32_16x16x32_bf16 v[72:75], v[158:161], v[210:213], v[72:75]
	v_mfma_f32_16x16x32_bf16 v[68:71], v[166:169], v[210:213], v[68:71]
	v_mfma_f32_16x16x32_bf16 v[120:123], v[162:165], v[184:187], v[120:123]
	v_mfma_f32_16x16x32_bf16 v[116:119], v[170:173], v[184:187], v[116:119]
	v_mfma_f32_16x16x32_bf16 v[104:107], v[162:165], v[192:195], v[104:107]
	v_mfma_f32_16x16x32_bf16 v[100:103], v[170:173], v[192:195], v[100:103]
	v_mfma_f32_16x16x32_bf16 v[88:91], v[162:165], v[206:209], v[88:91]
	v_mfma_f32_16x16x32_bf16 v[84:87], v[170:173], v[206:209], v[84:87]
	v_mfma_f32_16x16x32_bf16 v[72:75], v[162:165], v[214:217], v[72:75]
	v_mfma_f32_16x16x32_bf16 v[68:71], v[170:173], v[214:217], v[68:71]
	s_setprio 0
	s_barrier
	s_add_i32 s62, s72, s71
	v_lshl_add_u64 v[174:175], v[174:175], 0, s[30:31]
	s_mov_b32 m0, s62
	ds_read_b128 v[180:183], v144 offset:49152
	ds_read_b128 v[184:187], v144 offset:50176
	ds_read_b128 v[188:191], v144 offset:51200
	ds_read_b128 v[192:195], v144 offset:52224
	ds_read_b128 v[196:199], v144 offset:53248
	ds_read_b128 v[206:209], v144 offset:54272
	ds_read_b128 v[210:213], v144 offset:55296
	ds_read_b128 v[214:217], v144 offset:56320
	global_load_lds_dwordx4 v[174:175], off
	s_add_i32 m0, s62, 0x2000
	s_add_u32 s24, s24, 0x40080
	v_lshl_add_u64 v[174:175], v[218:219], 0, s[30:31]
	s_addc_u32 s25, s25, 0
	s_add_i32 s62, s73, s71
	global_load_lds_dwordx4 v[174:175], off
	v_lshl_add_u64 v[174:175], s[24:25], 0, v[132:133]
	s_mov_b32 m0, s62
	s_nop 0
	global_load_lds_dwordx4 v[174:175], off
	v_lshl_add_u64 v[174:175], s[24:25], 0, v[0:1]
	s_add_i32 m0, s62, 0x2000
	s_nop 0
	global_load_lds_dwordx4 v[174:175], off
	v_lshl_add_u64 v[174:175], v[220:221], 0, s[30:31]
	s_mov_b32 m0, s26
	s_nop 0
	global_load_lds_dwordx4 v[174:175], off
	v_lshl_add_u64 v[174:175], v[222:223], 0, s[30:31]
	s_mov_b32 m0, s88
	s_nop 0
	global_load_lds_dwordx4 v[174:175], off
	s_waitcnt vmcnt(8)
	s_waitcnt lgkmcnt(0)
	s_barrier
	s_setprio 1
	v_mfma_f32_16x16x32_bf16 v[64:67], v[138:141], v[180:183], v[64:67]
	v_mfma_f32_16x16x32_bf16 v[60:63], v[150:153], v[180:183], v[60:63]
	v_mfma_f32_16x16x32_bf16 v[48:51], v[138:141], v[188:191], v[48:51]
	v_mfma_f32_16x16x32_bf16 v[44:47], v[150:153], v[188:191], v[44:47]
	v_mfma_f32_16x16x32_bf16 v[32:35], v[138:141], v[196:199], v[32:35]
	v_mfma_f32_16x16x32_bf16 v[28:31], v[150:153], v[196:199], v[28:31]
	v_mfma_f32_16x16x32_bf16 v[16:19], v[138:141], v[210:213], v[16:19]
	v_mfma_f32_16x16x32_bf16 v[12:15], v[150:153], v[210:213], v[12:15]
	v_mfma_f32_16x16x32_bf16 v[64:67], v[146:149], v[184:187], v[64:67]
	v_mfma_f32_16x16x32_bf16 v[60:63], v[154:157], v[184:187], v[60:63]
	v_mfma_f32_16x16x32_bf16 v[48:51], v[146:149], v[192:195], v[48:51]
	v_mfma_f32_16x16x32_bf16 v[44:47], v[154:157], v[192:195], v[44:47]
	v_mfma_f32_16x16x32_bf16 v[32:35], v[146:149], v[206:209], v[32:35]
	v_mfma_f32_16x16x32_bf16 v[28:31], v[154:157], v[206:209], v[28:31]
	v_mfma_f32_16x16x32_bf16 v[16:19], v[146:149], v[214:217], v[16:19]
	v_mfma_f32_16x16x32_bf16 v[12:15], v[154:157], v[214:217], v[12:15]
	v_mfma_f32_16x16x32_bf16 v[56:59], v[158:161], v[180:183], v[56:59]
	v_mfma_f32_16x16x32_bf16 v[52:55], v[166:169], v[180:183], v[52:55]
	v_mfma_f32_16x16x32_bf16 v[40:43], v[158:161], v[188:191], v[40:43]
	v_mfma_f32_16x16x32_bf16 v[36:39], v[166:169], v[188:191], v[36:39]
	v_mfma_f32_16x16x32_bf16 v[24:27], v[158:161], v[196:199], v[24:27]
	v_mfma_f32_16x16x32_bf16 v[20:23], v[166:169], v[196:199], v[20:23]
	v_mfma_f32_16x16x32_bf16 v[8:11], v[158:161], v[210:213], v[8:11]
	v_mfma_f32_16x16x32_bf16 v[4:7], v[166:169], v[210:213], v[4:7]
	v_mfma_f32_16x16x32_bf16 v[56:59], v[162:165], v[184:187], v[56:59]
	v_mfma_f32_16x16x32_bf16 v[52:55], v[170:173], v[184:187], v[52:55]
	v_mfma_f32_16x16x32_bf16 v[40:43], v[162:165], v[192:195], v[40:43]
	v_mfma_f32_16x16x32_bf16 v[36:39], v[170:173], v[192:195], v[36:39]
	v_mfma_f32_16x16x32_bf16 v[24:27], v[162:165], v[206:209], v[24:27]
	v_mfma_f32_16x16x32_bf16 v[20:23], v[170:173], v[206:209], v[20:23]
	v_mfma_f32_16x16x32_bf16 v[8:11], v[162:165], v[214:217], v[8:11]
	v_mfma_f32_16x16x32_bf16 v[4:7], v[170:173], v[214:217], v[4:7]
	s_setprio 0
	s_barrier
	s_add_i32 s96, s96, 2
	s_add_u32 s94, s94, 0x100
	s_addc_u32 s95, s95, 0
	s_cmp_gt_u32 s96, 13
	s_mov_b64 s[62:63], s[64:65]
	s_cbranch_scc0 .LBB0_800
	s_and_b64 vcc, exec, s[52:53]
	s_cbranch_vccz .LBB0_803
	s_barrier

.LBB0_889:
	s_add_u32 s24, s28, 0xfffc0080
	s_addc_u32 s25, s29, -1
	s_add_i32 s72, 0, 0x10000
	s_cmp_eq_u32 s88, 12
	s_cselect_b32 s59, s53, s25
	s_cselect_b32 s58, s84, s24
	v_add_u32_e32 v149, s72, v146
	s_cselect_b32 s25, s51, s87
	s_cselect_b32 s24, s85, s86
	s_add_i32 s89, 0, 0x14000
	ds_read_b128 v[138:141], v149
	ds_read_b128 v[142:145], v149 offset:1024
	ds_read_b128 v[150:153], v149 offset:2048
	ds_read_b128 v[154:157], v149 offset:3072
	v_add_u32_e32 v149, s89, v146
	ds_read_b128 v[158:161], v149
	ds_read_b128 v[162:165], v149 offset:1024
	ds_read_b128 v[166:169], v149 offset:2048
	ds_read_b128 v[170:173], v149 offset:3072
	v_lshl_add_u64 v[174:175], s[28:29], 0, v[134:135]
	s_add_i32 m0, s64, 0xc000
	ds_read_b128 v[180:183], v148
	ds_read_b128 v[184:187], v148 offset:1024
	ds_read_b128 v[188:191], v148 offset:2048
	ds_read_b128 v[192:195], v148 offset:3072
	ds_read_b128 v[196:199], v148 offset:4096
	ds_read_b128 v[206:209], v148 offset:5120
	ds_read_b128 v[210:213], v148 offset:6144
	ds_read_b128 v[214:217], v148 offset:7168
	global_load_lds_dwordx4 v[174:175], off
	v_lshl_add_u64 v[174:175], s[28:29], 0, v[136:137]
	s_add_i32 m0, s64, 0xe000
	s_nop 0
	global_load_lds_dwordx4 v[174:175], off
	s_waitcnt vmcnt(8)
	s_waitcnt lgkmcnt(0)
	s_barrier
	s_setprio 1
	v_mfma_f32_16x16x32_bf16 v[128:131], v[138:141], v[180:183], v[128:131]
	v_mfma_f32_16x16x32_bf16 v[124:127], v[150:153], v[180:183], v[124:127]
	v_mfma_f32_16x16x32_bf16 v[112:115], v[138:141], v[188:191], v[112:115]
	v_mfma_f32_16x16x32_bf16 v[108:111], v[150:153], v[188:191], v[108:111]
	v_mfma_f32_16x16x32_bf16 v[96:99], v[138:141], v[196:199], v[96:99]
	v_mfma_f32_16x16x32_bf16 v[92:95], v[150:153], v[196:199], v[92:95]
	v_mfma_f32_16x16x32_bf16 v[80:83], v[138:141], v[210:213], v[80:83]
	v_mfma_f32_16x16x32_bf16 v[76:79], v[150:153], v[210:213], v[76:79]
	v_mfma_f32_16x16x32_bf16 v[128:131], v[142:145], v[184:187], v[128:131]
	v_mfma_f32_16x16x32_bf16 v[124:127], v[154:157], v[184:187], v[124:127]
	v_mfma_f32_16x16x32_bf16 v[112:115], v[142:145], v[192:195], v[112:115]
	v_mfma_f32_16x16x32_bf16 v[108:111], v[154:157], v[192:195], v[108:111]
	v_mfma_f32_16x16x32_bf16 v[96:99], v[142:145], v[206:209], v[96:99]
	v_mfma_f32_16x16x32_bf16 v[92:95], v[154:157], v[206:209], v[92:95]
	v_mfma_f32_16x16x32_bf16 v[80:83], v[142:145], v[214:217], v[80:83]
	v_mfma_f32_16x16x32_bf16 v[76:79], v[154:157], v[214:217], v[76:79]
	v_mfma_f32_16x16x32_bf16 v[120:123], v[158:161], v[180:183], v[120:123]
	v_mfma_f32_16x16x32_bf16 v[116:119], v[166:169], v[180:183], v[116:119]
	v_mfma_f32_16x16x32_bf16 v[104:107], v[158:161], v[188:191], v[104:107]
	v_mfma_f32_16x16x32_bf16 v[100:103], v[166:169], v[188:191], v[100:103]
	v_mfma_f32_16x16x32_bf16 v[88:91], v[158:161], v[196:199], v[88:91]
	v_mfma_f32_16x16x32_bf16 v[84:87], v[166:169], v[196:199], v[84:87]
	v_mfma_f32_16x16x32_bf16 v[72:75], v[158:161], v[210:213], v[72:75]
	v_mfma_f32_16x16x32_bf16 v[68:71], v[166:169], v[210:213], v[68:71]
	v_mfma_f32_16x16x32_bf16 v[120:123], v[162:165], v[184:187], v[120:123]
	v_mfma_f32_16x16x32_bf16 v[116:119], v[170:173], v[184:187], v[116:119]
	v_mfma_f32_16x16x32_bf16 v[104:107], v[162:165], v[192:195], v[104:107]
	v_mfma_f32_16x16x32_bf16 v[100:103], v[170:173], v[192:195], v[100:103]
	v_mfma_f32_16x16x32_bf16 v[88:91], v[162:165], v[206:209], v[88:91]
	v_mfma_f32_16x16x32_bf16 v[84:87], v[170:173], v[206:209], v[84:87]
	v_mfma_f32_16x16x32_bf16 v[72:75], v[162:165], v[214:217], v[72:75]
	v_mfma_f32_16x16x32_bf16 v[68:71], v[170:173], v[214:217], v[68:71]
	s_setprio 0
	s_barrier
	s_add_i32 s72, s72, s63
	v_lshl_add_u64 v[174:175], s[24:25], 0, v[132:133]
	s_mov_b32 m0, s72
	ds_read_b128 v[180:183], v148 offset:16384
	ds_read_b128 v[184:187], v148 offset:17408
	ds_read_b128 v[188:191], v148 offset:18432
	ds_read_b128 v[192:195], v148 offset:19456
	ds_read_b128 v[196:199], v148 offset:20480
	ds_read_b128 v[206:209], v148 offset:21504
	ds_read_b128 v[210:213], v148 offset:22528
	ds_read_b128 v[214:217], v148 offset:23552
	global_load_lds_dwordx4 v[174:175], off
	s_add_i32 m0, s72, 0x2000
	s_add_u32 s72, s24, 0x40000
	v_lshl_add_u64 v[218:219], s[24:25], 0, v[0:1]
	s_addc_u32 s73, s25, 0
	s_add_i32 s89, s89, s63
	global_load_lds_dwordx4 v[218:219], off
	v_lshl_add_u64 v[220:221], s[72:73], 0, v[132:133]
	s_mov_b32 m0, s89
	v_lshl_add_u64 v[222:223], s[58:59], 0, v[0:1]
	global_load_lds_dwordx4 v[220:221], off
	v_lshl_add_u64 v[220:221], s[72:73], 0, v[0:1]
	s_add_i32 m0, s89, 0x2000
	s_nop 0
	global_load_lds_dwordx4 v[220:221], off
	v_lshl_add_u64 v[220:221], s[58:59], 0, v[132:133]
	s_mov_b32 m0, s64
	s_nop 0
	global_load_lds_dwordx4 v[220:221], off
	s_mov_b32 m0, s65
	s_nop 0
	global_load_lds_dwordx4 v[222:223], off
	s_waitcnt vmcnt(8)
	s_waitcnt lgkmcnt(0)
	s_barrier
	s_setprio 1
	v_mfma_f32_16x16x32_bf16 v[64:67], v[138:141], v[180:183], v[64:67]
	v_mfma_f32_16x16x32_bf16 v[60:63], v[150:153], v[180:183], v[60:63]
	v_mfma_f32_16x16x32_bf16 v[48:51], v[138:141], v[188:191], v[48:51]
	v_mfma_f32_16x16x32_bf16 v[44:47], v[150:153], v[188:191], v[44:47]
	v_mfma_f32_16x16x32_bf16 v[32:35], v[138:141], v[196:199], v[32:35]
	v_mfma_f32_16x16x32_bf16 v[28:31], v[150:153], v[196:199], v[28:31]
	v_mfma_f32_16x16x32_bf16 v[16:19], v[138:141], v[210:213], v[16:19]
	v_mfma_f32_16x16x32_bf16 v[12:15], v[150:153], v[210:213], v[12:15]
	v_mfma_f32_16x16x32_bf16 v[64:67], v[142:145], v[184:187], v[64:67]
	v_mfma_f32_16x16x32_bf16 v[60:63], v[154:157], v[184:187], v[60:63]
	v_mfma_f32_16x16x32_bf16 v[48:51], v[142:145], v[192:195], v[48:51]
	v_mfma_f32_16x16x32_bf16 v[44:47], v[154:157], v[192:195], v[44:47]
	v_mfma_f32_16x16x32_bf16 v[32:35], v[142:145], v[206:209], v[32:35]
	v_mfma_f32_16x16x32_bf16 v[28:31], v[154:157], v[206:209], v[28:31]
	v_mfma_f32_16x16x32_bf16 v[16:19], v[142:145], v[214:217], v[16:19]
	v_mfma_f32_16x16x32_bf16 v[12:15], v[154:157], v[214:217], v[12:15]
	v_mfma_f32_16x16x32_bf16 v[56:59], v[158:161], v[180:183], v[56:59]
	v_mfma_f32_16x16x32_bf16 v[52:55], v[166:169], v[180:183], v[52:55]
	v_mfma_f32_16x16x32_bf16 v[40:43], v[158:161], v[188:191], v[40:43]
	v_mfma_f32_16x16x32_bf16 v[36:39], v[166:169], v[188:191], v[36:39]
	v_mfma_f32_16x16x32_bf16 v[24:27], v[158:161], v[196:199], v[24:27]
	v_mfma_f32_16x16x32_bf16 v[20:23], v[166:169], v[196:199], v[20:23]
	v_mfma_f32_16x16x32_bf16 v[8:11], v[158:161], v[210:213], v[8:11]
	v_mfma_f32_16x16x32_bf16 v[4:7], v[166:169], v[210:213], v[4:7]
	v_mfma_f32_16x16x32_bf16 v[56:59], v[162:165], v[184:187], v[56:59]
	v_mfma_f32_16x16x32_bf16 v[52:55], v[170:173], v[184:187], v[52:55]
	v_mfma_f32_16x16x32_bf16 v[40:43], v[162:165], v[192:195], v[40:43]
	v_mfma_f32_16x16x32_bf16 v[36:39], v[170:173], v[192:195], v[36:39]
	v_mfma_f32_16x16x32_bf16 v[24:27], v[162:165], v[206:209], v[24:27]
	v_mfma_f32_16x16x32_bf16 v[20:23], v[170:173], v[206:209], v[20:23]
	v_mfma_f32_16x16x32_bf16 v[8:11], v[162:165], v[214:217], v[8:11]
	v_mfma_f32_16x16x32_bf16 v[4:7], v[170:173], v[214:217], v[4:7]
	s_setprio 0
	s_barrier
	s_add_i32 s72, 0, 0x18000
	v_add_u32_e32 v149, s72, v146
	s_add_i32 s73, 0, 0x1c000
	ds_read_b128 v[138:141], v149
	ds_read_b128 v[142:145], v149 offset:1024
	ds_read_b128 v[150:153], v149 offset:2048
	ds_read_b128 v[154:157], v149 offset:3072
	v_add_u32_e32 v149, s73, v146
	ds_read_b128 v[158:161], v149
	ds_read_b128 v[162:165], v149 offset:1024
	ds_read_b128 v[166:169], v149 offset:2048
	ds_read_b128 v[170:173], v149 offset:3072
	s_add_u32 s58, s58, 0x40000
	s_addc_u32 s59, s59, 0
	s_mov_b32 m0, s66
	v_lshl_add_u64 v[224:225], s[58:59], 0, v[132:133]
	ds_read_b128 v[180:183], v148 offset:32768
	ds_read_b128 v[184:187], v148 offset:33792
	ds_read_b128 v[188:191], v148 offset:34816
	ds_read_b128 v[192:195], v148 offset:35840
	ds_read_b128 v[196:199], v148 offset:36864
	ds_read_b128 v[206:209], v148 offset:37888
	ds_read_b128 v[210:213], v148 offset:38912
	ds_read_b128 v[214:217], v148 offset:39936
	global_load_lds_dwordx4 v[224:225], off
	v_lshl_add_u64 v[224:225], s[58:59], 0, v[0:1]
	s_mov_b32 m0, s67
	s_nop 0
	global_load_lds_dwordx4 v[224:225], off
	s_waitcnt vmcnt(8)
	s_waitcnt lgkmcnt(0)
	s_barrier
	s_setprio 1
	v_mfma_f32_16x16x32_bf16 v[128:131], v[138:141], v[180:183], v[128:131]
	v_mfma_f32_16x16x32_bf16 v[124:127], v[150:153], v[180:183], v[124:127]
	v_mfma_f32_16x16x32_bf16 v[112:115], v[138:141], v[188:191], v[112:115]
	v_mfma_f32_16x16x32_bf16 v[108:111], v[150:153], v[188:191], v[108:111]
	v_mfma_f32_16x16x32_bf16 v[96:99], v[138:141], v[196:199], v[96:99]
	v_mfma_f32_16x16x32_bf16 v[92:95], v[150:153], v[196:199], v[92:95]
	v_mfma_f32_16x16x32_bf16 v[80:83], v[138:141], v[210:213], v[80:83]
	v_mfma_f32_16x16x32_bf16 v[76:79], v[150:153], v[210:213], v[76:79]
	v_mfma_f32_16x16x32_bf16 v[128:131], v[142:145], v[184:187], v[128:131]
	v_mfma_f32_16x16x32_bf16 v[124:127], v[154:157], v[184:187], v[124:127]
	v_mfma_f32_16x16x32_bf16 v[112:115], v[142:145], v[192:195], v[112:115]
	v_mfma_f32_16x16x32_bf16 v[108:111], v[154:157], v[192:195], v[108:111]
	v_mfma_f32_16x16x32_bf16 v[96:99], v[142:145], v[206:209], v[96:99]
	v_mfma_f32_16x16x32_bf16 v[92:95], v[154:157], v[206:209], v[92:95]
	v_mfma_f32_16x16x32_bf16 v[80:83], v[142:145], v[214:217], v[80:83]
	v_mfma_f32_16x16x32_bf16 v[76:79], v[154:157], v[214:217], v[76:79]
	v_mfma_f32_16x16x32_bf16 v[120:123], v[158:161], v[180:183], v[120:123]
	v_mfma_f32_16x16x32_bf16 v[116:119], v[166:169], v[180:183], v[116:119]
	v_mfma_f32_16x16x32_bf16 v[104:107], v[158:161], v[188:191], v[104:107]
	v_mfma_f32_16x16x32_bf16 v[100:103], v[166:169], v[188:191], v[100:103]
	v_mfma_f32_16x16x32_bf16 v[88:91], v[158:161], v[196:199], v[88:91]
	v_mfma_f32_16x16x32_bf16 v[84:87], v[166:169], v[196:199], v[84:87]
	v_mfma_f32_16x16x32_bf16 v[72:75], v[158:161], v[210:213], v[72:75]
	v_mfma_f32_16x16x32_bf16 v[68:71], v[166:169], v[210:213], v[68:71]
	v_mfma_f32_16x16x32_bf16 v[120:123], v[162:165], v[184:187], v[120:123]
	v_mfma_f32_16x16x32_bf16 v[116:119], v[170:173], v[184:187], v[116:119]
	v_mfma_f32_16x16x32_bf16 v[104:107], v[162:165], v[192:195], v[104:107]
	v_mfma_f32_16x16x32_bf16 v[100:103], v[170:173], v[192:195], v[100:103]
	v_mfma_f32_16x16x32_bf16 v[88:91], v[162:165], v[206:209], v[88:91]
	v_mfma_f32_16x16x32_bf16 v[84:87], v[170:173], v[206:209], v[84:87]
	v_mfma_f32_16x16x32_bf16 v[72:75], v[162:165], v[214:217], v[72:75]
	v_mfma_f32_16x16x32_bf16 v[68:71], v[170:173], v[214:217], v[68:71]
	s_setprio 0
	s_barrier
	s_add_i32 s58, s72, s63
	v_lshl_add_u64 v[174:175], v[174:175], 0, s[30:31]
	s_mov_b32 m0, s58
	ds_read_b128 v[180:183], v148 offset:49152
	ds_read_b128 v[184:187], v148 offset:50176
	ds_read_b128 v[188:191], v148 offset:51200
	ds_read_b128 v[192:195], v148 offset:52224
	ds_read_b128 v[196:199], v148 offset:53248
	ds_read_b128 v[206:209], v148 offset:54272
	ds_read_b128 v[210:213], v148 offset:55296
	ds_read_b128 v[214:217], v148 offset:56320
	global_load_lds_dwordx4 v[174:175], off
	s_add_i32 m0, s58, 0x2000
	s_add_u32 s24, s24, 0x40080
	v_lshl_add_u64 v[174:175], v[218:219], 0, s[30:31]
	s_addc_u32 s25, s25, 0
	s_add_i32 s58, s73, s63
	global_load_lds_dwordx4 v[174:175], off
	v_lshl_add_u64 v[174:175], s[24:25], 0, v[132:133]
	s_mov_b32 m0, s58
	s_nop 0
	global_load_lds_dwordx4 v[174:175], off
	v_lshl_add_u64 v[174:175], s[24:25], 0, v[0:1]
	s_add_i32 m0, s58, 0x2000
	s_nop 0
	global_load_lds_dwordx4 v[174:175], off
	v_lshl_add_u64 v[174:175], v[220:221], 0, s[30:31]
	s_mov_b32 m0, s26
	s_nop 0
	global_load_lds_dwordx4 v[174:175], off
	v_lshl_add_u64 v[174:175], v[222:223], 0, s[30:31]
	s_mov_b32 m0, s68
	s_nop 0
	global_load_lds_dwordx4 v[174:175], off
	s_waitcnt vmcnt(8)
	s_waitcnt lgkmcnt(0)
	s_barrier
	s_setprio 1
	v_mfma_f32_16x16x32_bf16 v[64:67], v[138:141], v[180:183], v[64:67]
	v_mfma_f32_16x16x32_bf16 v[60:63], v[150:153], v[180:183], v[60:63]
	v_mfma_f32_16x16x32_bf16 v[48:51], v[138:141], v[188:191], v[48:51]
	v_mfma_f32_16x16x32_bf16 v[44:47], v[150:153], v[188:191], v[44:47]
	v_mfma_f32_16x16x32_bf16 v[32:35], v[138:141], v[196:199], v[32:35]
	v_mfma_f32_16x16x32_bf16 v[28:31], v[150:153], v[196:199], v[28:31]
	v_mfma_f32_16x16x32_bf16 v[16:19], v[138:141], v[210:213], v[16:19]
	v_mfma_f32_16x16x32_bf16 v[12:15], v[150:153], v[210:213], v[12:15]
	v_mfma_f32_16x16x32_bf16 v[64:67], v[142:145], v[184:187], v[64:67]
	v_mfma_f32_16x16x32_bf16 v[60:63], v[154:157], v[184:187], v[60:63]
	v_mfma_f32_16x16x32_bf16 v[48:51], v[142:145], v[192:195], v[48:51]
	v_mfma_f32_16x16x32_bf16 v[44:47], v[154:157], v[192:195], v[44:47]
	v_mfma_f32_16x16x32_bf16 v[32:35], v[142:145], v[206:209], v[32:35]
	v_mfma_f32_16x16x32_bf16 v[28:31], v[154:157], v[206:209], v[28:31]
	v_mfma_f32_16x16x32_bf16 v[16:19], v[142:145], v[214:217], v[16:19]
	v_mfma_f32_16x16x32_bf16 v[12:15], v[154:157], v[214:217], v[12:15]
	v_mfma_f32_16x16x32_bf16 v[56:59], v[158:161], v[180:183], v[56:59]
	v_mfma_f32_16x16x32_bf16 v[52:55], v[166:169], v[180:183], v[52:55]
	v_mfma_f32_16x16x32_bf16 v[40:43], v[158:161], v[188:191], v[40:43]
	v_mfma_f32_16x16x32_bf16 v[36:39], v[166:169], v[188:191], v[36:39]
	v_mfma_f32_16x16x32_bf16 v[24:27], v[158:161], v[196:199], v[24:27]
	v_mfma_f32_16x16x32_bf16 v[20:23], v[166:169], v[196:199], v[20:23]
	v_mfma_f32_16x16x32_bf16 v[8:11], v[158:161], v[210:213], v[8:11]
	v_mfma_f32_16x16x32_bf16 v[4:7], v[166:169], v[210:213], v[4:7]
	v_mfma_f32_16x16x32_bf16 v[56:59], v[162:165], v[184:187], v[56:59]
	v_mfma_f32_16x16x32_bf16 v[52:55], v[170:173], v[184:187], v[52:55]
	v_mfma_f32_16x16x32_bf16 v[40:43], v[162:165], v[192:195], v[40:43]
	v_mfma_f32_16x16x32_bf16 v[36:39], v[170:173], v[192:195], v[36:39]
	v_mfma_f32_16x16x32_bf16 v[24:27], v[162:165], v[206:209], v[24:27]
	v_mfma_f32_16x16x32_bf16 v[20:23], v[170:173], v[206:209], v[20:23]
	v_mfma_f32_16x16x32_bf16 v[8:11], v[162:165], v[214:217], v[8:11]
	v_mfma_f32_16x16x32_bf16 v[4:7], v[170:173], v[214:217], v[4:7]
	s_setprio 0
	s_barrier
	s_add_i32 s88, s88, 2
	s_add_u32 s28, s28, 0x100
	s_addc_u32 s29, s29, 0
	s_add_u32 s86, s86, 0x100
	s_addc_u32 s87, s87, 0
	s_cmp_gt_u32 s88, 13
	s_cbranch_scc0 .LBB0_889
	s_and_b64 vcc, exec, s[48:49]
	s_cbranch_vccz .LBB0_892
	s_barrier

.LBB0_961:
	s_add_u32 s60, s28, 0x100
	s_addc_u32 s61, s29, 0
	s_add_i32 s72, 0, 0x10000
	s_cmp_eq_u32 s92, 60
	s_cselect_b32 s63, s55, s61
	s_cselect_b32 s62, s88, s60
	v_add_u32_e32 v149, s72, v146
	s_cselect_b32 s25, s53, s91
	s_cselect_b32 s24, s89, s90
	s_add_i32 s73, 0, 0x14000
	ds_read_b128 v[138:141], v149
	ds_read_b128 v[142:145], v149 offset:1024
	ds_read_b128 v[150:153], v149 offset:2048
	ds_read_b128 v[154:157], v149 offset:3072
	v_add_u32_e32 v149, s73, v146
	ds_read_b128 v[158:161], v149
	ds_read_b128 v[162:165], v149 offset:1024
	ds_read_b128 v[166:169], v149 offset:2048
	ds_read_b128 v[170:173], v149 offset:3072
	v_lshl_add_u64 v[174:175], s[28:29], 0, v[134:135]
	s_add_i32 m0, s67, 0xc000
	ds_read_b128 v[180:183], v148
	ds_read_b128 v[184:187], v148 offset:1024
	ds_read_b128 v[188:191], v148 offset:2048
	ds_read_b128 v[192:195], v148 offset:3072
	ds_read_b128 v[196:199], v148 offset:4096
	ds_read_b128 v[206:209], v148 offset:5120
	ds_read_b128 v[210:213], v148 offset:6144
	ds_read_b128 v[214:217], v148 offset:7168
	global_load_lds_dwordx4 v[174:175], off
	v_lshl_add_u64 v[174:175], s[28:29], 0, v[136:137]
	s_add_i32 m0, s67, 0xe000
	s_nop 0
	global_load_lds_dwordx4 v[174:175], off
	s_waitcnt vmcnt(8)
	s_waitcnt lgkmcnt(0)
	s_barrier
	s_setprio 1
	v_mfma_f32_16x16x32_bf16 v[128:131], v[138:141], v[180:183], v[128:131]
	v_mfma_f32_16x16x32_bf16 v[124:127], v[150:153], v[180:183], v[124:127]
	v_mfma_f32_16x16x32_bf16 v[112:115], v[138:141], v[188:191], v[112:115]
	v_mfma_f32_16x16x32_bf16 v[108:111], v[150:153], v[188:191], v[108:111]
	v_mfma_f32_16x16x32_bf16 v[96:99], v[138:141], v[196:199], v[96:99]
	v_mfma_f32_16x16x32_bf16 v[92:95], v[150:153], v[196:199], v[92:95]
	v_mfma_f32_16x16x32_bf16 v[80:83], v[138:141], v[210:213], v[80:83]
	v_mfma_f32_16x16x32_bf16 v[76:79], v[150:153], v[210:213], v[76:79]
	v_mfma_f32_16x16x32_bf16 v[128:131], v[142:145], v[184:187], v[128:131]
	v_mfma_f32_16x16x32_bf16 v[124:127], v[154:157], v[184:187], v[124:127]
	v_mfma_f32_16x16x32_bf16 v[112:115], v[142:145], v[192:195], v[112:115]
	v_mfma_f32_16x16x32_bf16 v[108:111], v[154:157], v[192:195], v[108:111]
	v_mfma_f32_16x16x32_bf16 v[96:99], v[142:145], v[206:209], v[96:99]
	v_mfma_f32_16x16x32_bf16 v[92:95], v[154:157], v[206:209], v[92:95]
	v_mfma_f32_16x16x32_bf16 v[80:83], v[142:145], v[214:217], v[80:83]
	v_mfma_f32_16x16x32_bf16 v[76:79], v[154:157], v[214:217], v[76:79]
	v_mfma_f32_16x16x32_bf16 v[120:123], v[158:161], v[180:183], v[120:123]
	v_mfma_f32_16x16x32_bf16 v[116:119], v[166:169], v[180:183], v[116:119]
	v_mfma_f32_16x16x32_bf16 v[104:107], v[158:161], v[188:191], v[104:107]
	v_mfma_f32_16x16x32_bf16 v[100:103], v[166:169], v[188:191], v[100:103]
	v_mfma_f32_16x16x32_bf16 v[88:91], v[158:161], v[196:199], v[88:91]
	v_mfma_f32_16x16x32_bf16 v[84:87], v[166:169], v[196:199], v[84:87]
	v_mfma_f32_16x16x32_bf16 v[72:75], v[158:161], v[210:213], v[72:75]
	v_mfma_f32_16x16x32_bf16 v[68:71], v[166:169], v[210:213], v[68:71]
	v_mfma_f32_16x16x32_bf16 v[120:123], v[162:165], v[184:187], v[120:123]
	v_mfma_f32_16x16x32_bf16 v[116:119], v[170:173], v[184:187], v[116:119]
	v_mfma_f32_16x16x32_bf16 v[104:107], v[162:165], v[192:195], v[104:107]
	v_mfma_f32_16x16x32_bf16 v[100:103], v[170:173], v[192:195], v[100:103]
	v_mfma_f32_16x16x32_bf16 v[88:91], v[162:165], v[206:209], v[88:91]
	v_mfma_f32_16x16x32_bf16 v[84:87], v[170:173], v[206:209], v[84:87]
	v_mfma_f32_16x16x32_bf16 v[72:75], v[162:165], v[214:217], v[72:75]
	v_mfma_f32_16x16x32_bf16 v[68:71], v[170:173], v[214:217], v[68:71]
	s_setprio 0
	s_barrier
	s_add_i32 s28, s72, s66
	v_lshl_add_u64 v[174:175], s[24:25], 0, v[132:133]
	s_mov_b32 m0, s28
	ds_read_b128 v[180:183], v148 offset:16384
	ds_read_b128 v[184:187], v148 offset:17408
	ds_read_b128 v[188:191], v148 offset:18432
	ds_read_b128 v[192:195], v148 offset:19456
	ds_read_b128 v[196:199], v148 offset:20480
	ds_read_b128 v[206:209], v148 offset:21504
	ds_read_b128 v[210:213], v148 offset:22528
	ds_read_b128 v[214:217], v148 offset:23552
	global_load_lds_dwordx4 v[174:175], off
	s_add_i32 m0, s28, 0x2000
	s_add_u32 s28, s24, 0x100000
	v_lshl_add_u64 v[218:219], s[24:25], 0, v[0:1]
	s_addc_u32 s29, s25, 0
	s_add_i32 s72, s73, s66
	global_load_lds_dwordx4 v[218:219], off
	v_lshl_add_u64 v[220:221], s[28:29], 0, v[132:133]
	s_mov_b32 m0, s72
	v_lshl_add_u64 v[222:223], s[62:63], 0, v[0:1]
	global_load_lds_dwordx4 v[220:221], off
	v_lshl_add_u64 v[220:221], s[28:29], 0, v[0:1]
	s_add_i32 m0, s72, 0x2000
	s_nop 0
	global_load_lds_dwordx4 v[220:221], off
	v_lshl_add_u64 v[220:221], s[62:63], 0, v[132:133]
	s_mov_b32 m0, s67
	s_nop 0
	global_load_lds_dwordx4 v[220:221], off
	s_mov_b32 m0, s68
	s_nop 0
	global_load_lds_dwordx4 v[222:223], off
	s_waitcnt vmcnt(8)
	s_waitcnt lgkmcnt(0)
	s_barrier
	s_setprio 1
	v_mfma_f32_16x16x32_bf16 v[64:67], v[138:141], v[180:183], v[64:67]
	v_mfma_f32_16x16x32_bf16 v[60:63], v[150:153], v[180:183], v[60:63]
	v_mfma_f32_16x16x32_bf16 v[48:51], v[138:141], v[188:191], v[48:51]
	v_mfma_f32_16x16x32_bf16 v[44:47], v[150:153], v[188:191], v[44:47]
	v_mfma_f32_16x16x32_bf16 v[32:35], v[138:141], v[196:199], v[32:35]
	v_mfma_f32_16x16x32_bf16 v[28:31], v[150:153], v[196:199], v[28:31]
	v_mfma_f32_16x16x32_bf16 v[16:19], v[138:141], v[210:213], v[16:19]
	v_mfma_f32_16x16x32_bf16 v[12:15], v[150:153], v[210:213], v[12:15]
	v_mfma_f32_16x16x32_bf16 v[64:67], v[142:145], v[184:187], v[64:67]
	v_mfma_f32_16x16x32_bf16 v[60:63], v[154:157], v[184:187], v[60:63]
	v_mfma_f32_16x16x32_bf16 v[48:51], v[142:145], v[192:195], v[48:51]
	v_mfma_f32_16x16x32_bf16 v[44:47], v[154:157], v[192:195], v[44:47]
	v_mfma_f32_16x16x32_bf16 v[32:35], v[142:145], v[206:209], v[32:35]
	v_mfma_f32_16x16x32_bf16 v[28:31], v[154:157], v[206:209], v[28:31]
	v_mfma_f32_16x16x32_bf16 v[16:19], v[142:145], v[214:217], v[16:19]
	v_mfma_f32_16x16x32_bf16 v[12:15], v[154:157], v[214:217], v[12:15]
	v_mfma_f32_16x16x32_bf16 v[56:59], v[158:161], v[180:183], v[56:59]
	v_mfma_f32_16x16x32_bf16 v[52:55], v[166:169], v[180:183], v[52:55]
	v_mfma_f32_16x16x32_bf16 v[40:43], v[158:161], v[188:191], v[40:43]
	v_mfma_f32_16x16x32_bf16 v[36:39], v[166:169], v[188:191], v[36:39]
	v_mfma_f32_16x16x32_bf16 v[24:27], v[158:161], v[196:199], v[24:27]
	v_mfma_f32_16x16x32_bf16 v[20:23], v[166:169], v[196:199], v[20:23]
	v_mfma_f32_16x16x32_bf16 v[8:11], v[158:161], v[210:213], v[8:11]
	v_mfma_f32_16x16x32_bf16 v[4:7], v[166:169], v[210:213], v[4:7]
	v_mfma_f32_16x16x32_bf16 v[56:59], v[162:165], v[184:187], v[56:59]
	v_mfma_f32_16x16x32_bf16 v[52:55], v[170:173], v[184:187], v[52:55]
	v_mfma_f32_16x16x32_bf16 v[40:43], v[162:165], v[192:195], v[40:43]
	v_mfma_f32_16x16x32_bf16 v[36:39], v[170:173], v[192:195], v[36:39]
	v_mfma_f32_16x16x32_bf16 v[24:27], v[162:165], v[206:209], v[24:27]
	v_mfma_f32_16x16x32_bf16 v[20:23], v[170:173], v[206:209], v[20:23]
	v_mfma_f32_16x16x32_bf16 v[8:11], v[162:165], v[214:217], v[8:11]
	v_mfma_f32_16x16x32_bf16 v[4:7], v[170:173], v[214:217], v[4:7]
	s_setprio 0
	s_barrier
	s_add_i32 s72, 0, 0x18000
	v_add_u32_e32 v149, s72, v146
	s_add_i32 s73, 0, 0x1c000
	ds_read_b128 v[138:141], v149
	ds_read_b128 v[142:145], v149 offset:1024
	ds_read_b128 v[150:153], v149 offset:2048
	ds_read_b128 v[154:157], v149 offset:3072
	v_add_u32_e32 v149, s73, v146
	ds_read_b128 v[158:161], v149
	ds_read_b128 v[162:165], v149 offset:1024
	ds_read_b128 v[166:169], v149 offset:2048
	ds_read_b128 v[170:173], v149 offset:3072
	s_add_u32 s28, s62, 0x100000
	s_addc_u32 s29, s63, 0
	s_mov_b32 m0, s69
	v_lshl_add_u64 v[224:225], s[28:29], 0, v[132:133]
	ds_read_b128 v[180:183], v148 offset:32768
	ds_read_b128 v[184:187], v148 offset:33792
	ds_read_b128 v[188:191], v148 offset:34816
	ds_read_b128 v[192:195], v148 offset:35840
	ds_read_b128 v[196:199], v148 offset:36864
	ds_read_b128 v[206:209], v148 offset:37888
	ds_read_b128 v[210:213], v148 offset:38912
	ds_read_b128 v[214:217], v148 offset:39936
	global_load_lds_dwordx4 v[224:225], off
	v_lshl_add_u64 v[224:225], s[28:29], 0, v[0:1]
	s_mov_b32 m0, s70
	s_nop 0
	global_load_lds_dwordx4 v[224:225], off
	s_waitcnt vmcnt(8)
	s_waitcnt lgkmcnt(0)
	s_barrier
	s_setprio 1
	v_mfma_f32_16x16x32_bf16 v[128:131], v[138:141], v[180:183], v[128:131]
	v_mfma_f32_16x16x32_bf16 v[124:127], v[150:153], v[180:183], v[124:127]
	v_mfma_f32_16x16x32_bf16 v[112:115], v[138:141], v[188:191], v[112:115]
	v_mfma_f32_16x16x32_bf16 v[108:111], v[150:153], v[188:191], v[108:111]
	v_mfma_f32_16x16x32_bf16 v[96:99], v[138:141], v[196:199], v[96:99]
	v_mfma_f32_16x16x32_bf16 v[92:95], v[150:153], v[196:199], v[92:95]
	v_mfma_f32_16x16x32_bf16 v[80:83], v[138:141], v[210:213], v[80:83]
	v_mfma_f32_16x16x32_bf16 v[76:79], v[150:153], v[210:213], v[76:79]
	v_mfma_f32_16x16x32_bf16 v[128:131], v[142:145], v[184:187], v[128:131]
	v_mfma_f32_16x16x32_bf16 v[124:127], v[154:157], v[184:187], v[124:127]
	v_mfma_f32_16x16x32_bf16 v[112:115], v[142:145], v[192:195], v[112:115]
	v_mfma_f32_16x16x32_bf16 v[108:111], v[154:157], v[192:195], v[108:111]
	v_mfma_f32_16x16x32_bf16 v[96:99], v[142:145], v[206:209], v[96:99]
	v_mfma_f32_16x16x32_bf16 v[92:95], v[154:157], v[206:209], v[92:95]
	v_mfma_f32_16x16x32_bf16 v[80:83], v[142:145], v[214:217], v[80:83]
	v_mfma_f32_16x16x32_bf16 v[76:79], v[154:157], v[214:217], v[76:79]
	v_mfma_f32_16x16x32_bf16 v[120:123], v[158:161], v[180:183], v[120:123]
	v_mfma_f32_16x16x32_bf16 v[116:119], v[166:169], v[180:183], v[116:119]
	v_mfma_f32_16x16x32_bf16 v[104:107], v[158:161], v[188:191], v[104:107]
	v_mfma_f32_16x16x32_bf16 v[100:103], v[166:169], v[188:191], v[100:103]
	v_mfma_f32_16x16x32_bf16 v[88:91], v[158:161], v[196:199], v[88:91]
	v_mfma_f32_16x16x32_bf16 v[84:87], v[166:169], v[196:199], v[84:87]
	v_mfma_f32_16x16x32_bf16 v[72:75], v[158:161], v[210:213], v[72:75]
	v_mfma_f32_16x16x32_bf16 v[68:71], v[166:169], v[210:213], v[68:71]
	v_mfma_f32_16x16x32_bf16 v[120:123], v[162:165], v[184:187], v[120:123]
	v_mfma_f32_16x16x32_bf16 v[116:119], v[170:173], v[184:187], v[116:119]
	v_mfma_f32_16x16x32_bf16 v[104:107], v[162:165], v[192:195], v[104:107]
	v_mfma_f32_16x16x32_bf16 v[100:103], v[170:173], v[192:195], v[100:103]
	v_mfma_f32_16x16x32_bf16 v[88:91], v[162:165], v[206:209], v[88:91]
	v_mfma_f32_16x16x32_bf16 v[84:87], v[170:173], v[206:209], v[84:87]
	v_mfma_f32_16x16x32_bf16 v[72:75], v[162:165], v[214:217], v[72:75]
	v_mfma_f32_16x16x32_bf16 v[68:71], v[170:173], v[214:217], v[68:71]
	s_setprio 0
	s_barrier
	s_add_i32 s28, s72, s66
	v_lshl_add_u64 v[174:175], v[174:175], 0, s[30:31]
	s_mov_b32 m0, s28
	ds_read_b128 v[180:183], v148 offset:49152
	ds_read_b128 v[184:187], v148 offset:50176
	ds_read_b128 v[188:191], v148 offset:51200
	ds_read_b128 v[192:195], v148 offset:52224
	ds_read_b128 v[196:199], v148 offset:53248
	ds_read_b128 v[206:209], v148 offset:54272
	ds_read_b128 v[210:213], v148 offset:55296
	ds_read_b128 v[214:217], v148 offset:56320
	global_load_lds_dwordx4 v[174:175], off
	s_add_i32 m0, s28, 0x2000
	s_add_u32 s24, s24, 0x100080
	v_lshl_add_u64 v[174:175], v[218:219], 0, s[30:31]
	s_addc_u32 s25, s25, 0
	s_add_i32 s28, s73, s66
	global_load_lds_dwordx4 v[174:175], off
	v_lshl_add_u64 v[174:175], s[24:25], 0, v[132:133]
	s_mov_b32 m0, s28
	s_nop 0
	global_load_lds_dwordx4 v[174:175], off
	v_lshl_add_u64 v[174:175], s[24:25], 0, v[0:1]
	s_add_i32 m0, s28, 0x2000
	s_nop 0
	global_load_lds_dwordx4 v[174:175], off
	v_lshl_add_u64 v[174:175], v[220:221], 0, s[30:31]
	s_mov_b32 m0, s71
	s_nop 0
	global_load_lds_dwordx4 v[174:175], off
	v_lshl_add_u64 v[174:175], v[222:223], 0, s[30:31]
	s_mov_b32 m0, s84
	s_nop 0
	global_load_lds_dwordx4 v[174:175], off
	s_waitcnt vmcnt(8)
	s_waitcnt lgkmcnt(0)
	s_barrier
	s_setprio 1
	v_mfma_f32_16x16x32_bf16 v[64:67], v[138:141], v[180:183], v[64:67]
	v_mfma_f32_16x16x32_bf16 v[60:63], v[150:153], v[180:183], v[60:63]
	v_mfma_f32_16x16x32_bf16 v[48:51], v[138:141], v[188:191], v[48:51]
	v_mfma_f32_16x16x32_bf16 v[44:47], v[150:153], v[188:191], v[44:47]
	v_mfma_f32_16x16x32_bf16 v[32:35], v[138:141], v[196:199], v[32:35]
	v_mfma_f32_16x16x32_bf16 v[28:31], v[150:153], v[196:199], v[28:31]
	v_mfma_f32_16x16x32_bf16 v[16:19], v[138:141], v[210:213], v[16:19]
	v_mfma_f32_16x16x32_bf16 v[12:15], v[150:153], v[210:213], v[12:15]
	v_mfma_f32_16x16x32_bf16 v[64:67], v[142:145], v[184:187], v[64:67]
	v_mfma_f32_16x16x32_bf16 v[60:63], v[154:157], v[184:187], v[60:63]
	v_mfma_f32_16x16x32_bf16 v[48:51], v[142:145], v[192:195], v[48:51]
	v_mfma_f32_16x16x32_bf16 v[44:47], v[154:157], v[192:195], v[44:47]
	v_mfma_f32_16x16x32_bf16 v[32:35], v[142:145], v[206:209], v[32:35]
	v_mfma_f32_16x16x32_bf16 v[28:31], v[154:157], v[206:209], v[28:31]
	v_mfma_f32_16x16x32_bf16 v[16:19], v[142:145], v[214:217], v[16:19]
	v_mfma_f32_16x16x32_bf16 v[12:15], v[154:157], v[214:217], v[12:15]
	v_mfma_f32_16x16x32_bf16 v[56:59], v[158:161], v[180:183], v[56:59]
	v_mfma_f32_16x16x32_bf16 v[52:55], v[166:169], v[180:183], v[52:55]
	v_mfma_f32_16x16x32_bf16 v[40:43], v[158:161], v[188:191], v[40:43]
	v_mfma_f32_16x16x32_bf16 v[36:39], v[166:169], v[188:191], v[36:39]
	v_mfma_f32_16x16x32_bf16 v[24:27], v[158:161], v[196:199], v[24:27]
	v_mfma_f32_16x16x32_bf16 v[20:23], v[166:169], v[196:199], v[20:23]
	v_mfma_f32_16x16x32_bf16 v[8:11], v[158:161], v[210:213], v[8:11]
	v_mfma_f32_16x16x32_bf16 v[4:7], v[166:169], v[210:213], v[4:7]
	v_mfma_f32_16x16x32_bf16 v[56:59], v[162:165], v[184:187], v[56:59]
	v_mfma_f32_16x16x32_bf16 v[52:55], v[170:173], v[184:187], v[52:55]
	v_mfma_f32_16x16x32_bf16 v[40:43], v[162:165], v[192:195], v[40:43]
	v_mfma_f32_16x16x32_bf16 v[36:39], v[170:173], v[192:195], v[36:39]
	v_mfma_f32_16x16x32_bf16 v[24:27], v[162:165], v[206:209], v[24:27]
	v_mfma_f32_16x16x32_bf16 v[20:23], v[170:173], v[206:209], v[20:23]
	v_mfma_f32_16x16x32_bf16 v[8:11], v[162:165], v[214:217], v[8:11]
	v_mfma_f32_16x16x32_bf16 v[4:7], v[170:173], v[214:217], v[4:7]
	s_setprio 0
	s_barrier
	s_add_i32 s92, s92, 2
	s_add_u32 s90, s90, 0x100
	s_addc_u32 s91, s91, 0
	s_cmp_gt_u32 s92, 61
	s_mov_b64 s[28:29], s[60:61]
	s_cbranch_scc0 .LBB0_961
	s_and_b64 vcc, exec, s[50:51]
	s_cbranch_vccz .LBB0_964
	s_barrier
